# v206 + P1 prologue: rows-per-wave division 16384/(8*G) replaced by the constant 8 (grid is fixed at 256)
# speedup vs baseline: 1.0041x; 1.0013x over previous
.LBB0_75:
	s_add_u32 s16, s58, 0x2c00000
	s_addc_u32 s79, s59, 0
	s_cmp_lt_i32 s60, 2
	s_cselect_b64 s[2:3], -1, 0
	s_cmp_gt_i32 s61, 1
	s_cselect_b64 s[4:5], -1, 0
	s_and_b64 s[2:3], s[2:3], s[4:5]
	s_andn2_b64 vcc, exec, s[2:3]
	v_writelane_b32 v254, s34, 21
	s_cbranch_vccnz .LBB0_115
	s_mov_b32 s15, 0
	s_mov_b32 s14, 8
	s_cmp_lt_i32 s14, 1
	s_cbranch_scc1 .LBB0_79
	v_readlane_b32 s2, v254, 18
	v_readlane_b32 s3, v254, 19
	s_lshl_b32 s2, s2, 3
	v_readlane_b32 s3, v254, 20
	s_add_i32 s2, s2, s3
	s_mul_i32 s2, s14, s2
	s_ashr_i32 s3, s2, 31
	s_lshr_b32 s4, s3, 20
	s_add_i32 s4, s2, s4
	s_ashr_i32 s4, s4, 12
	s_mulk_i32 s4, 0x2400
	s_ashr_i32 s5, s4, 31
	s_lshl_b64 s[4:5], s[4:5], 2
	s_add_u32 s0, s0, s4
	s_addc_u32 s1, s1, s5
	s_add_u32 s4, s0, 0x1000
	s_waitcnt vmcnt(8)
	v_lshlrev_b32_e32 v50, 5, v1
	s_addc_u32 s5, s1, 0
	v_or_b32_e32 v2, 0x800, v50
	global_load_dwordx4 v[18:21], v50, s[4:5]
	global_load_dwordx4 v[22:25], v50, s[4:5] offset:16
	global_load_dwordx4 v[26:29], v2, s[4:5]
	global_load_dwordx4 v[30:33], v2, s[4:5] offset:16
	v_readlane_b32 s80, v254, 2
	v_readlane_b32 s88, v254, 10
	v_readlane_b32 s89, v254, 11
	v_readlane_b32 s90, v254, 12
	v_readlane_b32 s91, v254, 13
	v_readlane_b32 s92, v254, 14
	v_readlane_b32 s93, v254, 15
	v_readlane_b32 s94, v254, 16
	v_readlane_b32 s95, v254, 17
	s_mov_b64 s[20:21], s[88:89]
	global_load_dwordx4 v[34:37], v50, s[20:21]
	global_load_dwordx4 v[38:41], v50, s[20:21] offset:16
	global_load_dwordx4 v[42:45], v50, s[20:21] offset:2048
	global_load_dwordx4 v[46:49], v50, s[20:21] offset:2064
	global_load_dwordx4 v[2:5], v50, s[0:1] offset:16
	global_load_dwordx4 v[6:9], v50, s[0:1]
	global_load_dwordx4 v[10:13], v50, s[0:1] offset:2064
	global_load_dwordx4 v[14:17], v50, s[0:1] offset:2048
	s_waitcnt vmcnt(17)
	v_mbcnt_lo_u32_b32 v52, -1, 0
	v_mbcnt_hi_u32_b32 v52, -1, v52
	v_and_b32_e32 v54, 64, v52
	v_xor_b32_e32 v55, 1, v52
	v_add_u32_e32 v54, 64, v54
	s_waitcnt vmcnt(16)
	v_lshlrev_b32_e32 v53, 4, v1
	v_xor_b32_e32 v56, 2, v52
	v_cmp_lt_i32_e32 vcc, v55, v54
	v_xor_b32_e32 v57, 4, v52
	v_lshl_or_b32 v70, s2, 11, v53
	v_cndmask_b32_e32 v53, v52, v55, vcc
	v_cmp_lt_i32_e32 vcc, v56, v54
	v_readlane_b32 s81, v254, 3
	v_xor_b32_e32 v58, 8, v52
	v_cndmask_b32_e32 v55, v52, v56, vcc
	v_cmp_lt_i32_e32 vcc, v57, v54
	s_mov_b64 s[12:13], s[80:81]
	v_xor_b32_e32 v59, 16, v52
	v_cndmask_b32_e32 v56, v52, v57, vcc
	v_cmp_lt_i32_e32 vcc, v58, v54
	s_and_b32 s17, s79, 0xffff
	s_lshl_b64 s[2:3], s[2:3], 12
	v_xor_b32_e32 v60, 32, v52
	v_cndmask_b32_e32 v57, v52, v58, vcc
	v_cmp_lt_i32_e32 vcc, v59, v54
	s_add_u32 s2, s12, s2
	v_mov_b32_e32 v51, 0
	v_cndmask_b32_e32 v58, v52, v59, vcc
	v_cmp_lt_i32_e32 vcc, v60, v54
	s_addc_u32 s3, s13, s3
	s_mov_b64 s[0:1], 0x1000
	v_cndmask_b32_e32 v52, v52, v60, vcc
	v_lshl_add_u64 v[50:51], s[2:3], 0, v[50:51]
	s_mov_b32 s19, 0x20000
	s_brev_b32 s18, 64
	v_mov_b32_e32 v68, 0x358637bd
	s_mov_b32 s20, 0xf800000
	v_mov_b32_e32 v69, 0x260
	v_lshlrev_b32_e32 v71, 2, v53
	v_lshlrev_b32_e32 v72, 2, v55
	v_lshlrev_b32_e32 v73, 2, v56
	v_lshlrev_b32_e32 v74, 2, v57
	v_lshlrev_b32_e32 v75, 2, v58
	v_lshlrev_b32_e32 v76, 2, v52
	v_lshl_add_u64 v[50:51], v[50:51], 0, s[0:1]
	s_mov_b64 s[6:7], 0x2000
	v_readlane_b32 s82, v254, 4
	v_readlane_b32 s83, v254, 5
	v_readlane_b32 s84, v254, 6
	v_readlane_b32 s85, v254, 7
	v_readlane_b32 s86, v254, 8
	v_readlane_b32 s87, v254, 9
	s_mov_b64 s[22:23], s[90:91]
	s_mov_b64 s[24:25], s[92:93]
	s_mov_b64 s[26:27], s[94:95]
	s_waitcnt vmcnt(11)
	v_pk_add_f32 v[20:21], v[20:21], 1.0 op_sel_hi:[1,0]
	v_pk_add_f32 v[18:19], v[18:19], 1.0 op_sel_hi:[1,0]
	s_waitcnt vmcnt(10)
	v_pk_add_f32 v[24:25], v[24:25], 1.0 op_sel_hi:[1,0]
	v_pk_add_f32 v[22:23], v[22:23], 1.0 op_sel_hi:[1,0]
	s_waitcnt vmcnt(9)
	v_pk_add_f32 v[28:29], v[28:29], 1.0 op_sel_hi:[1,0]
	v_pk_add_f32 v[26:27], v[26:27], 1.0 op_sel_hi:[1,0]
	s_waitcnt vmcnt(8)
	v_pk_add_f32 v[32:33], v[32:33], 1.0 op_sel_hi:[1,0]
	v_pk_add_f32 v[30:31], v[30:31], 1.0 op_sel_hi:[1,0]
	s_waitcnt vmcnt(7)
	v_pk_mul_f32 v[52:53], v[36:37], v[20:21]
	v_pk_mul_f32 v[54:55], v[34:35], v[18:19]
	s_waitcnt vmcnt(6)
	v_pk_mul_f32 v[56:57], v[40:41], v[24:25]
	v_pk_mul_f32 v[58:59], v[38:39], v[22:23]
	s_waitcnt vmcnt(5)
	v_pk_mul_f32 v[60:61], v[44:45], v[28:29]
	v_pk_mul_f32 v[62:63], v[42:43], v[26:27]
	s_waitcnt vmcnt(4)
	v_pk_mul_f32 v[64:65], v[48:49], v[32:33]
	v_pk_mul_f32 v[66:67], v[46:47], v[30:31]
